# nt hint also on the bf16 residual-mirror (x16) stores and the f32 x loads of the post-mix row phase
# baseline (speedup 1.0000x reference)
.LBB0_269:
	s_or_b64 exec, exec, s[0:1]
	v_lshlrev_b64 v[82:83], 2, v[46:47]
	v_lshl_add_u64 v[32:33], s[28:29], 0, v[82:83]
	global_load_dwordx4 v[90:93], v[32:33], off
	global_load_dwordx4 v[94:97], v[32:33], off offset:1024
	global_load_dwordx4 v[98:101], v[32:33], off offset:2048
	global_load_dwordx4 v[102:105], v[32:33], off offset:3072
	v_add_co_u32_e32 v32, vcc, s30, v32
	v_readlane_b32 s0, v255, 8
	s_nop 0
	v_addc_co_u32_e32 v33, vcc, 0, v33, vcc
	global_load_dwordx4 v[106:109], v[32:33], off
	global_load_dwordx4 v[110:113], v[32:33], off offset:1024
	global_load_dwordx4 v[114:117], v[32:33], off offset:2048
	global_load_dwordx4 v[118:121], v[32:33], off offset:3072
	v_min_i32_e32 v32, 0x2000, v44
	v_ashrrev_i32_e32 v32, 11, v32
	v_mul_hi_i32_i24_e32 v41, 0xc000, v32
	v_mul_i32_i24_e32 v40, 0xc000, v32
	v_readlane_b32 s1, v255, 9
	v_lshl_add_u64 v[86:87], s[34:35], 0, v[82:83]
	global_load_dwordx4 v[36:39], v[86:87], off
	global_load_dwordx4 v[32:35], v[86:87], off offset:1024
	v_lshl_add_u64 v[40:41], s[0:1], 0, v[40:41]
	v_lshl_add_u64 v[84:85], v[40:41], 0, v[82:83]
	s_mov_b64 s[0:1], 0x4000
	v_lshl_add_u64 v[130:131], v[84:85], 0, s[0:1]
	s_movk_i32 s0, 0x5000
	v_add_co_u32_e32 v132, vcc, s0, v84
	s_movk_i32 s0, 0x7000
	s_nop 0
	v_addc_co_u32_e32 v133, vcc, 0, v85, vcc
	global_load_dwordx4 v[122:125], v[132:133], off offset:-4096
	global_load_dwordx4 v[126:129], v[130:131], off offset:1024
	global_load_dwordx4 v[40:43], v[130:131], off offset:2048
	v_lshlrev_b64 v[46:47], 1, v[46:47]
	s_waitcnt vmcnt(0)
	v_pk_add_f32 v[134:135], v[50:51], v[92:93]
	v_pk_add_f32 v[136:137], v[48:49], v[90:91]
	v_pk_add_f32 v[138:139], v[54:55], v[96:97]
	v_pk_add_f32 v[140:141], v[52:53], v[94:95]
	v_pk_add_f32 v[142:143], v[58:59], v[100:101]
	v_pk_add_f32 v[144:145], v[56:57], v[98:99]
	v_pk_add_f32 v[148:149], v[60:61], v[102:103]
	v_pk_add_f32 v[60:61], v[66:67], v[108:109]
	v_pk_add_f32 v[56:57], v[70:71], v[112:113]
	v_mov_b32_e32 v66, v137
	v_mov_b32_e32 v67, v141
	v_mov_b32_e32 v70, v135
	v_mov_b32_e32 v71, v139
	v_pk_add_f32 v[146:147], v[62:63], v[104:105]
	v_pk_add_f32 v[62:63], v[64:65], v[106:107]
	v_pk_add_f32 v[58:59], v[68:69], v[110:111]
	v_pk_add_f32 v[52:53], v[74:75], v[116:117]
	v_pk_add_f32 v[54:55], v[72:73], v[114:115]
	v_mov_b32_e32 v64, v136
	v_mov_b32_e32 v65, v140
	v_mov_b32_e32 v68, v134
	v_mov_b32_e32 v69, v138
	v_pk_mul_f32 v[72:73], v[144:145], v[144:145]
	v_pk_mul_f32 v[74:75], v[142:143], v[142:143]
	v_pk_mul_f32 v[66:67], v[66:67], v[66:67]
	v_pk_mul_f32 v[70:71], v[70:71], v[70:71]
	v_pk_mov_b32 v[90:91], v[72:73], v[74:75] op_sel:[1,0]
	v_mov_b32_e32 v73, v75
	v_pk_fma_f32 v[64:65], v[64:65], v[64:65], v[66:67]
	v_pk_fma_f32 v[66:67], v[68:69], v[68:69], v[70:71]
	v_pk_add_f32 v[48:49], v[78:79], v[120:121]
	v_pk_add_f32 v[50:51], v[76:77], v[118:119]
	v_mul_f32_e32 v76, v149, v149
	v_mul_f32_e32 v78, v147, v147
	v_pk_add_f32 v[68:69], v[90:91], v[72:73]
	v_pk_add_f32 v[64:65], v[64:65], v[66:67]
	v_mul_f32_e32 v45, v62, v62
	v_mul_f32_e32 v89, v63, v63
	v_mul_f32_e32 v94, v60, v60
	v_mul_f32_e32 v95, v61, v61
	v_pk_fma_f32 v[74:75], v[148:149], v[148:149], v[76:77] op_sel_hi:[1,1,0]
	v_pk_fma_f32 v[76:77], v[146:147], v[146:147], v[78:79] op_sel_hi:[1,1,0]
	v_pk_add_f32 v[66:67], v[68:69], v[68:69] op_sel:[0,1] op_sel_hi:[1,0]
	v_pk_add_f32 v[64:65], v[64:65], v[64:65] op_sel:[0,1] op_sel_hi:[1,0]
	v_pk_mul_f32 v[78:79], v[56:57], v[56:57]
	v_pk_mul_f32 v[92:93], v[58:59], v[58:59]
	v_mov_b32_e32 v75, v94
	v_mov_b32_e32 v77, v95
	v_mov_b32_e32 v67, v89
	v_mov_b32_e32 v65, v45
	v_pk_mov_b32 v[70:71], v[92:93], v[78:79] op_sel:[1,0]
	v_mov_b32_e32 v93, v79
	v_pk_add_f32 v[68:69], v[74:75], v[76:77]
	v_pk_add_f32 v[64:65], v[64:65], v[66:67]
	v_pk_add_f32 v[70:71], v[70:71], v[92:93]
	v_pk_add_f32 v[64:65], v[64:65], v[68:69]
	v_mul_f32_e32 v96, v50, v50
	v_mul_f32_e32 v97, v51, v51
	v_pk_add_f32 v[64:65], v[64:65], v[64:65] op_sel:[0,1] op_sel_hi:[1,0]
	v_pk_add_f32 v[66:67], v[70:71], v[70:71] op_sel:[0,1] op_sel_hi:[1,0]
	v_mov_b32_e32 v65, v96
	v_mov_b32_e32 v67, v97
	v_pk_add_f32 v[64:65], v[64:65], v[66:67]
	v_mul_f32_e32 v66, v55, v55
	v_mul_f32_e32 v68, v53, v53
	v_mul_f32_e32 v98, v48, v48
	v_mul_f32_e32 v99, v49, v49
	v_pk_fma_f32 v[66:67], v[54:55], v[54:55], v[66:67] op_sel_hi:[1,1,0]
	v_pk_fma_f32 v[68:69], v[52:53], v[52:53], v[68:69] op_sel_hi:[1,1,0]
	v_mov_b32_e32 v67, v98
	v_mov_b32_e32 v69, v99
	v_pk_add_f32 v[66:67], v[66:67], v[68:69]
	s_nop 0
	v_pk_add_f32 v[64:65], v[64:65], v[66:67]
	s_nop 0
	v_add_f32_e32 v45, v64, v65
	v_and_b32_e32 v64, 64, v229
	v_add_u32_e32 v89, 64, v64
	v_xor_b32_e32 v64, 1, v229
	v_cmp_lt_i32_e32 vcc, v64, v89
	s_nop 1
	v_cndmask_b32_e32 v64, v229, v64, vcc
	v_lshlrev_b32_e32 v150, 2, v64
	ds_bpermute_b32 v90, v150, v45
	global_load_dwordx4 v[64:67], v[130:131], off offset:3072
	global_load_dwordx4 v[68:71], v[86:87], off offset:2048
	global_load_dwordx4 v[72:75], v[86:87], off offset:3072
	global_load_dwordx4 v[76:79], v[132:133], off
	s_waitcnt lgkmcnt(0)
	v_add_f32_e32 v45, v45, v90
	v_xor_b32_e32 v90, 2, v229
	v_cmp_lt_i32_e32 vcc, v90, v89
	s_nop 1
	v_cndmask_b32_e32 v90, v229, v90, vcc
	v_add_co_u32_e32 v86, vcc, s30, v86
	v_lshlrev_b32_e32 v151, 2, v90
	s_nop 0
	v_addc_co_u32_e32 v87, vcc, 0, v87, vcc
	ds_bpermute_b32 v98, v151, v45
	global_load_dwordx4 v[90:93], v[86:87], off
	global_load_dwordx4 v[94:97], v[86:87], off offset:1024
	s_waitcnt lgkmcnt(0)
	v_add_f32_e32 v45, v45, v98
	v_xor_b32_e32 v98, 4, v229
	v_cmp_lt_i32_e32 vcc, v98, v89
	s_nop 1
	v_cndmask_b32_e32 v98, v229, v98, vcc
	v_lshlrev_b32_e32 v152, 2, v98
	ds_bpermute_b32 v114, v152, v45
	global_load_dwordx4 v[98:101], v[132:133], off offset:1024
	global_load_dwordx4 v[102:105], v[132:133], off offset:2048
	global_load_dwordx4 v[106:109], v[86:87], off offset:2048
	global_load_dwordx4 v[110:113], v[86:87], off offset:3072
	v_xor_b32_e32 v86, 8, v229
	v_cmp_lt_i32_e32 vcc, v86, v89
	s_waitcnt lgkmcnt(0)
	v_add_f32_e32 v45, v45, v114
	global_load_dwordx4 v[114:117], v[132:133], off offset:3072
	v_cndmask_b32_e32 v86, v229, v86, vcc
	v_lshlrev_b32_e32 v153, 2, v86
	ds_bpermute_b32 v86, v153, v45
	s_waitcnt lgkmcnt(0)
	v_add_f32_e32 v45, v45, v86
	v_xor_b32_e32 v86, 16, v229
	v_cmp_lt_i32_e32 vcc, v86, v89
	s_nop 1
	v_cndmask_b32_e32 v86, v229, v86, vcc
	v_lshlrev_b32_e32 v132, 2, v86
	ds_bpermute_b32 v86, v132, v45
	s_waitcnt lgkmcnt(0)
	v_add_f32_e32 v45, v45, v86
	v_xor_b32_e32 v86, 32, v229
	v_cmp_lt_i32_e32 vcc, v86, v89
	s_nop 1
	v_cndmask_b32_e32 v86, v229, v86, vcc
	v_lshlrev_b32_e32 v89, 2, v86
	ds_bpermute_b32 v86, v89, v45
	s_waitcnt lgkmcnt(0)
	v_add_f32_e32 v45, v45, v86
	v_fmamk_f32 v45, v45, 0x3a000000, v227
	v_mul_f32_e32 v86, 0x4b800000, v45
	v_cmp_gt_f32_e32 vcc, s96, v45
	s_nop 1
	v_cndmask_b32_e32 v45, v45, v86, vcc
	v_rsq_f32_e32 v45, v45
	s_nop 0
	v_mul_f32_e32 v86, 0x45800000, v45
	v_cndmask_b32_e32 v86, v45, v86, vcc
	v_pk_mul_f32 v[118:119], v[134:135], v[86:87] op_sel_hi:[1,0]
	v_pk_mul_f32 v[120:121], v[136:137], v[86:87] op_sel_hi:[1,0]
	v_pk_mul_f32 v[38:39], v[38:39], v[118:119]
	v_pk_mul_f32 v[36:37], v[36:37], v[120:121]
	v_pk_fma_f32 v[30:31], v[124:125], v[38:39], v[30:31]
	v_pk_mul_f32 v[38:39], v[140:141], v[86:87] op_sel_hi:[1,0]
	v_pk_fma_f32 v[28:29], v[122:123], v[36:37], v[28:29]
	v_pk_mul_f32 v[32:33], v[32:33], v[38:39]
	v_pk_mul_f32 v[36:37], v[138:139], v[86:87] op_sel_hi:[1,0]
	v_pk_fma_f32 v[24:25], v[126:127], v[32:33], v[24:25]
	v_pk_mul_f32 v[32:33], v[142:143], v[86:87] op_sel_hi:[1,0]
	v_pk_mul_f32 v[34:35], v[34:35], v[36:37]
	s_waitcnt vmcnt(9)
	v_pk_mul_f32 v[32:33], v[70:71], v[32:33]
	v_pk_fma_f32 v[26:27], v[128:129], v[34:35], v[26:27]
	v_pk_fma_f32 v[18:19], v[42:43], v[32:33], v[18:19]
	v_pk_mul_f32 v[32:33], v[146:147], v[86:87] op_sel_hi:[1,0]
	v_pk_mul_f32 v[34:35], v[144:145], v[86:87] op_sel_hi:[1,0]
	s_waitcnt vmcnt(8)
	v_pk_mul_f32 v[32:33], v[74:75], v[32:33]
	v_pk_mul_f32 v[34:35], v[68:69], v[34:35]
	v_pk_fma_f32 v[10:11], v[66:67], v[32:33], v[10:11]
	v_pk_mul_f32 v[32:33], v[60:61], v[86:87] op_sel_hi:[1,0]
	v_pk_fma_f32 v[16:17], v[40:41], v[34:35], v[16:17]
	v_pk_mul_f32 v[34:35], v[148:149], v[86:87] op_sel_hi:[1,0]
	s_waitcnt vmcnt(6)
	v_pk_mul_f32 v[32:33], v[92:93], v[32:33]
	v_mov_b32_e32 v74, v29
	v_mov_b32_e32 v75, v25
	v_pk_mul_f32 v[34:35], v[72:73], v[34:35]
	v_pk_fma_f32 v[22:23], v[78:79], v[32:33], v[22:23]
	v_mov_b32_e32 v72, v28
	v_mov_b32_e32 v73, v24
	v_pk_mul_f32 v[74:75], v[74:75], v[74:75]
	v_mov_b32_e32 v78, v31
	v_mov_b32_e32 v79, v27
	v_pk_fma_f32 v[72:73], v[72:73], v[72:73], v[74:75]
	v_mov_b32_e32 v74, v30
	v_mov_b32_e32 v75, v26
	v_pk_mul_f32 v[78:79], v[78:79], v[78:79]
	v_pk_fma_f32 v[8:9], v[64:65], v[34:35], v[8:9]
	v_pk_fma_f32 v[74:75], v[74:75], v[74:75], v[78:79]
	v_pk_mul_f32 v[78:79], v[16:17], v[16:17]
	v_pk_add_f32 v[72:73], v[72:73], v[74:75]
	v_pk_mul_f32 v[74:75], v[18:19], v[18:19]
	v_pk_add_f32 v[72:73], v[72:73], v[72:73] op_sel_hi:[0,1]
	v_pk_mul_f32 v[34:35], v[62:63], v[86:87] op_sel_hi:[1,0]
	v_lshl_add_u64 v[92:93], s[38:39], 0, v[82:83]
	v_pk_mov_b32 v[82:83], v[78:79], v[74:75] op_sel:[1,0]
	v_mov_b32_e32 v79, v75
	v_mul_f32_e32 v72, v8, v8
	v_pk_mul_f32 v[34:35], v[90:91], v[34:35]
	v_pk_add_f32 v[74:75], v[82:83], v[78:79]
	v_pk_fma_f32 v[78:79], v[8:9], v[8:9], v[72:73] op_sel_hi:[1,1,0]
	v_mul_f32_e32 v72, v10, v10
	v_pk_fma_f32 v[20:21], v[76:77], v[34:35], v[20:21]
	v_pk_mul_f32 v[34:35], v[58:59], v[86:87] op_sel_hi:[1,0]
	v_pk_add_f32 v[74:75], v[74:75], v[74:75] op_sel_hi:[0,1]
	v_pk_fma_f32 v[82:83], v[10:11], v[10:11], v[72:73] op_sel_hi:[1,1,0]
	v_pk_mul_f32 v[32:33], v[56:57], v[86:87] op_sel_hi:[1,0]
	s_waitcnt vmcnt(5)
	v_pk_mul_f32 v[34:35], v[94:95], v[34:35]
	v_mul_f32_e32 v78, v20, v20
	v_mul_f32_e32 v82, v21, v21
	v_mul_f32_e32 v74, v22, v22
	v_mul_f32_e32 v72, v23, v23
	v_pk_mul_f32 v[32:33], v[96:97], v[32:33]
	s_waitcnt vmcnt(4)
	v_pk_fma_f32 v[12:13], v[98:99], v[34:35], v[12:13]
	v_pk_mul_f32 v[34:35], v[54:55], v[86:87] op_sel_hi:[1,0]
	v_pk_add_f32 v[78:79], v[78:79], v[82:83]
	v_pk_add_f32 v[72:73], v[74:75], v[72:73]
	v_pk_fma_f32 v[14:15], v[100:101], v[32:33], v[14:15]
	v_pk_mul_f32 v[32:33], v[52:53], v[86:87] op_sel_hi:[1,0]
	s_waitcnt vmcnt(2)
	v_pk_mul_f32 v[34:35], v[106:107], v[34:35]
	v_pk_add_f32 v[72:73], v[78:79], v[72:73]
	v_pk_mul_f32 v[32:33], v[108:109], v[32:33]
	v_pk_fma_f32 v[4:5], v[102:103], v[34:35], v[4:5]
	v_pk_add_f32 v[72:73], v[72:73], v[72:73] op_sel_hi:[0,1]
	v_pk_mul_f32 v[74:75], v[14:15], v[14:15]
	v_pk_mul_f32 v[78:79], v[12:13], v[12:13]
	v_pk_fma_f32 v[6:7], v[104:105], v[32:33], v[6:7]
	v_pk_mul_f32 v[32:33], v[48:49], v[86:87] op_sel_hi:[1,0]
	v_pk_mul_f32 v[34:35], v[50:51], v[86:87] op_sel_hi:[1,0]
	v_pk_mov_b32 v[82:83], v[78:79], v[74:75] op_sel:[1,0]
	v_mov_b32_e32 v79, v75
	v_mul_f32_e32 v72, v4, v4
	s_waitcnt vmcnt(1)
	v_pk_mul_f32 v[36:37], v[110:111], v[34:35]
	v_pk_mul_f32 v[38:39], v[112:113], v[32:33]
	v_pk_add_f32 v[74:75], v[82:83], v[78:79]
	v_pk_fma_f32 v[78:79], v[4:5], v[4:5], v[72:73] op_sel_hi:[1,1,0]
	v_mul_f32_e32 v72, v6, v6
	s_waitcnt vmcnt(0)
	v_pk_fma_f32 v[2:3], v[116:117], v[38:39], v[2:3]
	v_pk_fma_f32 v[0:1], v[114:115], v[36:37], v[0:1]
	v_pk_add_f32 v[74:75], v[74:75], v[74:75] op_sel_hi:[0,1]
	v_pk_fma_f32 v[82:83], v[6:7], v[6:7], v[72:73] op_sel_hi:[1,1,0]
	v_mul_f32_e32 v78, v0, v0
	v_mul_f32_e32 v82, v1, v1
	v_mul_f32_e32 v74, v2, v2
	v_mul_f32_e32 v72, v3, v3
	v_pk_add_f32 v[78:79], v[78:79], v[82:83]
	v_pk_add_f32 v[72:73], v[74:75], v[72:73]
	v_add_co_u32_e32 v86, vcc, s0, v84
	v_pk_add_f32 v[72:73], v[78:79], v[72:73]
	s_nop 0
	v_addc_co_u32_e32 v87, vcc, 0, v85, vcc
	v_add_f32_e32 v45, v72, v73
	ds_bpermute_b32 v94, v150, v45
	global_load_dwordx4 v[32:35], v[86:87], off offset:-4096
	s_mov_b64 s[0:1], 0x6000
	v_lshl_add_u64 v[90:91], v[84:85], 0, s[0:1]
	s_mov_b64 s[0:1], 0x8000
	s_waitcnt lgkmcnt(0)
	v_add_f32_e32 v45, v45, v94
	ds_bpermute_b32 v102, v151, v45
	v_lshl_add_u64 v[76:77], v[84:85], 0, s[0:1]
	s_mov_b32 s0, 0x9000
	v_add_co_u32_e32 v130, vcc, s0, v84
	s_waitcnt lgkmcnt(0)
	v_add_f32_e32 v45, v45, v102
	ds_bpermute_b32 v106, v152, v45
	v_addc_co_u32_e32 v131, vcc, 0, v85, vcc
	global_load_dwordx4 v[36:39], v[130:131], off offset:-4096
	global_load_dwordx4 v[40:43], v[92:93], off
	global_load_dwordx4 v[48:51], v[92:93], off offset:1024
	global_load_dwordx4 v[52:55], v[76:77], off offset:1024
	global_load_dwordx4 v[56:59], v[92:93], off offset:2048
	global_load_dwordx4 v[60:63], v[90:91], off offset:1024
	global_load_dwordx4 v[64:67], v[90:91], off offset:2048
	global_load_dwordx4 v[68:71], v[76:77], off offset:2048
	global_load_dwordx4 v[72:75], v[92:93], off offset:3072
	s_nop 0
	global_load_dwordx4 v[76:79], v[76:77], off offset:3072
	s_nop 0
	global_load_dwordx4 v[82:85], v[90:91], off offset:3072
	s_waitcnt lgkmcnt(0)
	v_add_f32_e32 v45, v45, v106
	v_add_co_u32_e32 v126, vcc, s30, v92
	ds_bpermute_b32 v114, v153, v45
	s_nop 0
	v_addc_co_u32_e32 v127, vcc, 0, v93, vcc
	global_load_dwordx4 v[90:93], v[126:127], off
	global_load_dwordx4 v[94:97], v[86:87], off
	global_load_dwordx4 v[98:101], v[130:131], off
	global_load_dwordx4 v[102:105], v[126:127], off offset:1024
	s_waitcnt lgkmcnt(0)
	v_add_f32_e32 v45, v45, v114
	global_load_dwordx4 v[106:109], v[130:131], off offset:1024
	global_load_dwordx4 v[110:113], v[86:87], off offset:1024
	ds_bpermute_b32 v122, v132, v45
	global_load_dwordx4 v[114:117], v[126:127], off offset:2048
	global_load_dwordx4 v[118:121], v[130:131], off offset:2048
	v_readlane_b32 s0, v253, 31
	v_readlane_b32 s1, v253, 32
	s_waitcnt lgkmcnt(0)
	v_add_f32_e32 v45, v45, v122
	global_load_dwordx4 v[122:125], v[86:87], off offset:2048
	s_nop 0
	global_load_dwordx4 v[126:129], v[126:127], off offset:3072
	s_nop 0
	global_load_dwordx4 v[130:133], v[130:131], off offset:3072
	ds_bpermute_b32 v89, v89, v45
	global_load_dwordx4 v[134:137], v[86:87], off offset:3072
	s_waitcnt lgkmcnt(0)
	v_add_f32_e32 v45, v45, v89
	v_fmamk_f32 v45, v45, 0x3a000000, v227
	v_mul_f32_e32 v89, 0x4b800000, v45
	v_cmp_gt_f32_e32 vcc, s96, v45
	s_waitcnt vmcnt(22)
	v_pk_add_f32 v[38:39], v[38:39], 1.0 op_sel_hi:[1,0]
	v_cndmask_b32_e32 v45, v45, v89, vcc
	v_rsq_f32_e32 v45, v45
	v_pk_add_f32 v[36:37], v[36:37], 1.0 op_sel_hi:[1,0]
	v_mul_f32_e32 v86, 0x45800000, v45
	v_cndmask_b32_e32 v86, v45, v86, vcc
	v_pk_mul_f32 v[138:139], v[30:31], v[86:87] op_sel_hi:[1,0]
	v_pk_mul_f32 v[140:141], v[28:29], v[86:87] op_sel_hi:[1,0]
	s_waitcnt vmcnt(21)
	v_pk_mul_f32 v[42:43], v[42:43], v[138:139]
	v_pk_mul_f32 v[40:41], v[40:41], v[140:141]
	v_pk_fma_f32 v[34:35], v[38:39], v[42:43], v[34:35]
	v_pk_fma_f32 v[32:33], v[36:37], v[40:41], v[32:33]
	v_pk_mul_f32 v[36:37], v[24:25], v[86:87] op_sel_hi:[1,0]
	v_cvt_pk_bf16_f32 v32, v32, v33
	v_cvt_pk_bf16_f32 v33, v34, v35
	v_pk_mul_f32 v[34:35], v[26:27], v[86:87] op_sel_hi:[1,0]
	s_waitcnt vmcnt(20)
	v_pk_mul_f32 v[36:37], v[48:49], v[36:37]
	v_pk_mul_f32 v[34:35], v[50:51], v[34:35]
	s_waitcnt vmcnt(19)
	v_pk_add_f32 v[38:39], v[54:55], 1.0 op_sel_hi:[1,0]
	v_pk_add_f32 v[40:41], v[52:53], 1.0 op_sel_hi:[1,0]
	s_waitcnt vmcnt(17)
	v_pk_fma_f32 v[34:35], v[38:39], v[34:35], v[62:63]
	v_pk_fma_f32 v[36:37], v[40:41], v[36:37], v[60:61]
	v_pk_mul_f32 v[38:39], v[16:17], v[86:87] op_sel_hi:[1,0]
	v_cvt_pk_bf16_f32 v36, v36, v37
	v_cvt_pk_bf16_f32 v37, v34, v35
	v_pk_mul_f32 v[34:35], v[18:19], v[86:87] op_sel_hi:[1,0]
	v_pk_mul_f32 v[38:39], v[56:57], v[38:39]
	v_pk_mul_f32 v[34:35], v[58:59], v[34:35]
	s_waitcnt vmcnt(15)
	v_pk_add_f32 v[40:41], v[70:71], 1.0 op_sel_hi:[1,0]
	v_pk_add_f32 v[42:43], v[68:69], 1.0 op_sel_hi:[1,0]
	v_pk_fma_f32 v[34:35], v[40:41], v[34:35], v[66:67]
	v_pk_fma_f32 v[38:39], v[42:43], v[38:39], v[64:65]
	v_pk_mul_f32 v[40:41], v[8:9], v[86:87] op_sel_hi:[1,0]
	v_cvt_pk_bf16_f32 v38, v38, v39
	v_cvt_pk_bf16_f32 v39, v34, v35
	v_pk_mul_f32 v[34:35], v[10:11], v[86:87] op_sel_hi:[1,0]
	s_waitcnt vmcnt(14)
	v_pk_mul_f32 v[40:41], v[72:73], v[40:41]
	v_pk_mul_f32 v[34:35], v[74:75], v[34:35]
	s_waitcnt vmcnt(13)
	v_pk_add_f32 v[42:43], v[78:79], 1.0 op_sel_hi:[1,0]
	v_pk_add_f32 v[48:49], v[76:77], 1.0 op_sel_hi:[1,0]
	s_waitcnt vmcnt(12)
	v_pk_fma_f32 v[34:35], v[42:43], v[34:35], v[84:85]
	v_pk_fma_f32 v[40:41], v[48:49], v[40:41], v[82:83]
	v_pk_mul_f32 v[42:43], v[20:21], v[86:87] op_sel_hi:[1,0]
	v_cvt_pk_bf16_f32 v40, v40, v41
	v_cvt_pk_bf16_f32 v41, v34, v35
	v_pk_mul_f32 v[34:35], v[22:23], v[86:87] op_sel_hi:[1,0]
	s_waitcnt vmcnt(11)
	v_pk_mul_f32 v[42:43], v[90:91], v[42:43]
	v_pk_mul_f32 v[34:35], v[92:93], v[34:35]
	s_waitcnt vmcnt(9)
	v_pk_add_f32 v[48:49], v[100:101], 1.0 op_sel_hi:[1,0]
	v_pk_add_f32 v[50:51], v[98:99], 1.0 op_sel_hi:[1,0]
	v_pk_fma_f32 v[34:35], v[48:49], v[34:35], v[96:97]
	v_pk_fma_f32 v[42:43], v[50:51], v[42:43], v[94:95]
	v_pk_mul_f32 v[48:49], v[12:13], v[86:87] op_sel_hi:[1,0]
	v_cvt_pk_bf16_f32 v42, v42, v43
	v_cvt_pk_bf16_f32 v43, v34, v35
	v_pk_mul_f32 v[34:35], v[14:15], v[86:87] op_sel_hi:[1,0]
	s_waitcnt vmcnt(8)
	v_pk_mul_f32 v[48:49], v[102:103], v[48:49]
	v_pk_mul_f32 v[34:35], v[104:105], v[34:35]
	s_waitcnt vmcnt(7)
	v_pk_add_f32 v[50:51], v[108:109], 1.0 op_sel_hi:[1,0]
	v_pk_add_f32 v[52:53], v[106:107], 1.0 op_sel_hi:[1,0]
	s_waitcnt vmcnt(6)
	v_pk_fma_f32 v[34:35], v[50:51], v[34:35], v[112:113]
	v_pk_fma_f32 v[48:49], v[52:53], v[48:49], v[110:111]
	v_pk_mul_f32 v[50:51], v[4:5], v[86:87] op_sel_hi:[1,0]
	v_cvt_pk_bf16_f32 v48, v48, v49
	v_cvt_pk_bf16_f32 v49, v34, v35
	v_pk_mul_f32 v[34:35], v[6:7], v[86:87] op_sel_hi:[1,0]
	s_waitcnt vmcnt(5)
	v_pk_mul_f32 v[50:51], v[114:115], v[50:51]
	v_pk_mul_f32 v[34:35], v[116:117], v[34:35]
	s_waitcnt vmcnt(4)
	v_pk_add_f32 v[52:53], v[120:121], 1.0 op_sel_hi:[1,0]
	v_pk_add_f32 v[54:55], v[118:119], 1.0 op_sel_hi:[1,0]
	s_waitcnt vmcnt(3)
	v_pk_fma_f32 v[34:35], v[52:53], v[34:35], v[124:125]
	v_pk_fma_f32 v[50:51], v[54:55], v[50:51], v[122:123]
	v_pk_mul_f32 v[52:53], v[0:1], v[86:87] op_sel_hi:[1,0]
	v_cvt_pk_bf16_f32 v50, v50, v51
	v_cvt_pk_bf16_f32 v51, v34, v35
	v_pk_mul_f32 v[34:35], v[2:3], v[86:87] op_sel_hi:[1,0]
	s_waitcnt vmcnt(2)
	v_pk_mul_f32 v[52:53], v[126:127], v[52:53]
	v_pk_mul_f32 v[34:35], v[128:129], v[34:35]
	s_waitcnt vmcnt(1)
	v_pk_add_f32 v[54:55], v[132:133], 1.0 op_sel_hi:[1,0]
	v_pk_add_f32 v[56:57], v[130:131], 1.0 op_sel_hi:[1,0]
	s_waitcnt vmcnt(0)
	v_pk_fma_f32 v[34:35], v[54:55], v[34:35], v[136:137]
	v_pk_fma_f32 v[52:53], v[56:57], v[52:53], v[134:135]
	s_nop 0
	v_cvt_pk_bf16_f32 v52, v52, v53
	v_cvt_pk_bf16_f32 v53, v34, v35
	v_lshl_add_u64 v[34:35], s[0:1], 0, v[80:81]
	v_readlane_b32 s0, v252, 26
	v_lshl_add_u64 v[34:35], v[34:35], 0, v[46:47]
	v_readlane_b32 s1, v252, 27
	global_store_dwordx2 v[34:35], v[32:33], off
	global_store_dwordx2 v[34:35], v[36:37], off offset:512
	global_store_dwordx2 v[34:35], v[38:39], off offset:1024
	global_store_dwordx2 v[34:35], v[40:41], off offset:1536
	global_store_dwordx2 v[34:35], v[42:43], off offset:2048
	global_store_dwordx2 v[34:35], v[48:49], off offset:2560
	global_store_dwordx2 v[34:35], v[50:51], off offset:3072
	global_store_dwordx2 v[34:35], v[52:53], off offset:3584
	v_cvt_pk_bf16_f32 v28, v28, v29
	v_cvt_pk_bf16_f32 v29, v30, v31
	v_lshl_add_u64 v[30:31], s[0:1], 0, v[80:81]
	v_readlane_b32 s0, v254, 55
	v_lshl_add_u64 v[30:31], v[30:31], 0, v[46:47]
	global_store_dwordx2 v[30:31], v[28:29], off nt
	v_add_u32_e32 v44, s0, v44
	v_cvt_pk_bf16_f32 v24, v24, v25
	v_cvt_pk_bf16_f32 v25, v26, v27
	global_store_dwordx2 v[30:31], v[24:25], off offset:512 nt
	v_cvt_pk_bf16_f32 v16, v16, v17
	v_cvt_pk_bf16_f32 v17, v18, v19
	global_store_dwordx2 v[30:31], v[16:17], off offset:1024 nt
	v_cvt_pk_bf16_f32 v8, v8, v9
	v_cvt_pk_bf16_f32 v9, v10, v11
	v_cmp_le_i32_e32 vcc, s49, v44
	global_store_dwordx2 v[30:31], v[8:9], off offset:1536 nt
	v_cvt_pk_bf16_f32 v8, v20, v21
	v_cvt_pk_bf16_f32 v9, v22, v23
	s_or_b64 s[50:51], vcc, s[50:51]
	global_store_dwordx2 v[30:31], v[8:9], off offset:2048 nt
	v_cvt_pk_bf16_f32 v8, v12, v13
	v_cvt_pk_bf16_f32 v9, v14, v15
	global_store_dwordx2 v[30:31], v[8:9], off offset:2560 nt
	v_cvt_pk_bf16_f32 v4, v4, v5
	v_cvt_pk_bf16_f32 v5, v6, v7
	global_store_dwordx2 v[30:31], v[4:5], off offset:3072 nt
	v_cvt_pk_bf16_f32 v0, v0, v1
	v_cvt_pk_bf16_f32 v1, v2, v3
	v_readlane_b32 s1, v254, 56
	global_store_dwordx2 v[30:31], v[0:1], off offset:3584 nt
	s_andn2_b64 exec, exec, s[50:51]
	s_cbranch_execz .LBB0_290

.LBB0_273:
	v_readlane_b32 s80, v254, 18
	v_readlane_b32 s81, v254, 19
	v_readlane_b32 s85, v254, 23
	v_readlane_b32 s84, v254, 22
	v_mov_b32_e32 v1, s81
	v_mov_b32_e32 v0, s85
	v_cndmask_b32_e64 v1, v0, v1, s[36:37]
	v_mov_b32_e32 v0, s84
	v_mov_b32_e32 v2, s80
	v_cndmask_b32_e64 v0, v0, v2, s[36:37]
	v_cndmask_b32_e64 v3, 0, v45, s[36:37]
	v_cndmask_b32_e64 v2, v192, v44, s[36:37]
	v_lshlrev_b64 v[2:3], 13, v[2:3]
	v_lshl_add_u64 v[0:1], v[0:1], 0, v[2:3]
	v_lshl_add_u64 v[0:1], v[46:47], 2, v[0:1]
	global_load_dwordx4 v[28:31], v[0:1], off nt
	global_load_dwordx4 v[24:27], v[0:1], off offset:1024 nt
	global_load_dwordx4 v[16:19], v[0:1], off offset:2048 nt
	global_load_dwordx4 v[8:11], v[0:1], off offset:3072 nt
	v_add_co_u32_e32 v0, vcc, 0x1000, v0
	v_readlane_b32 s82, v254, 20
	s_nop 0
	v_addc_co_u32_e32 v1, vcc, 0, v1, vcc
	global_load_dwordx4 v[20:23], v[0:1], off nt
	global_load_dwordx4 v[12:15], v[0:1], off offset:1024 nt
	global_load_dwordx4 v[4:7], v[0:1], off offset:2048 nt
	s_nop 0
	global_load_dwordx4 v[0:3], v[0:1], off offset:3072 nt
	v_readlane_b32 s83, v254, 21
	v_readlane_b32 s86, v254, 24
	v_readlane_b32 s87, v254, 25
	v_readlane_b32 s88, v254, 26
	v_readlane_b32 s89, v254, 27
	v_readlane_b32 s90, v254, 28
	v_readlane_b32 s91, v254, 29
	v_readlane_b32 s92, v254, 30
	v_readlane_b32 s93, v254, 31
	v_readlane_b32 s94, v254, 32
	v_readlane_b32 s95, v254, 33

.LBB0_303:
	s_andn2_b64 vcc, exec, s[2:3]
	s_cbranch_vccnz .LBB0_295
	v_mov_b32_e32 v104, v1
	v_mov_b32_e32 v105, v5
	v_mov_b32_e32 v100, v0
	v_mov_b32_e32 v101, v4
	v_pk_mul_f32 v[104:105], v[104:105], v[104:105]
	v_mov_b32_e32 v106, v3
	v_mov_b32_e32 v107, v7
	v_pk_fma_f32 v[100:101], v[100:101], v[100:101], v[104:105]
	v_mov_b32_e32 v104, v2
	v_mov_b32_e32 v105, v6
	v_pk_mul_f32 v[106:107], v[106:107], v[106:107]
	v_lshl_add_u64 v[32:33], s[14:15], 0, v[40:41]
	v_pk_fma_f32 v[104:105], v[104:105], v[104:105], v[106:107]
	v_pk_mul_f32 v[106:107], v[8:9], v[8:9]
	v_pk_add_f32 v[100:101], v[100:101], v[104:105]
	v_pk_mul_f32 v[104:105], v[10:11], v[10:11]
	v_pk_add_f32 v[100:101], v[100:101], v[100:101] op_sel_hi:[0,1]
	v_pk_mov_b32 v[108:109], v[106:107], v[104:105] op_sel:[1,0]
	v_mov_b32_e32 v107, v105
	v_mul_f32_e32 v100, v12, v12
	v_pk_add_f32 v[104:105], v[108:109], v[106:107]
	v_pk_fma_f32 v[106:107], v[12:13], v[12:13], v[100:101] op_sel_hi:[1,1,0]
	v_mul_f32_e32 v100, v14, v14
	v_pk_add_f32 v[104:105], v[104:105], v[104:105] op_sel_hi:[0,1]
	v_pk_fma_f32 v[108:109], v[14:15], v[14:15], v[100:101] op_sel_hi:[1,1,0]
	v_mul_f32_e32 v106, v16, v16
	v_mul_f32_e32 v108, v17, v17
	v_mul_f32_e32 v104, v18, v18
	v_mul_f32_e32 v100, v19, v19
	v_pk_add_f32 v[106:107], v[106:107], v[108:109]
	v_pk_add_f32 v[100:101], v[104:105], v[100:101]
	v_pk_mul_f32 v[104:105], v[22:23], v[22:23]
	v_pk_add_f32 v[100:101], v[106:107], v[100:101]
	v_pk_mul_f32 v[106:107], v[20:21], v[20:21]
	v_pk_add_f32 v[100:101], v[100:101], v[100:101] op_sel_hi:[0,1]
	v_pk_mov_b32 v[108:109], v[106:107], v[104:105] op_sel:[1,0]
	v_mov_b32_e32 v107, v105
	v_mul_f32_e32 v100, v24, v24
	v_pk_add_f32 v[104:105], v[108:109], v[106:107]
	v_pk_fma_f32 v[106:107], v[24:25], v[24:25], v[100:101] op_sel_hi:[1,1,0]
	v_mul_f32_e32 v100, v26, v26
	v_pk_add_f32 v[104:105], v[104:105], v[104:105] op_sel_hi:[0,1]
	v_pk_fma_f32 v[108:109], v[26:27], v[26:27], v[100:101] op_sel_hi:[1,1,0]
	v_mul_f32_e32 v106, v28, v28
	v_mul_f32_e32 v108, v29, v29
	v_mul_f32_e32 v104, v30, v30
	v_mul_f32_e32 v100, v31, v31
	v_pk_add_f32 v[106:107], v[106:107], v[108:109]
	v_pk_add_f32 v[100:101], v[104:105], v[100:101]
	v_lshl_add_u64 v[102:103], v[32:33], 0, v[42:43]
	v_pk_add_f32 v[100:101], v[106:107], v[100:101]
	v_add_co_u32_e32 v36, vcc, 0x2000, v102
	v_add_f32_e32 v85, v100, v101
	ds_bpermute_b32 v104, v98, v85
	v_lshl_add_u64 v[34:35], s[12:13], 0, v[42:43]
	v_addc_co_u32_e32 v37, vcc, 0, v103, vcc
	v_add_co_u32_e32 v126, vcc, s30, v34
	s_waitcnt lgkmcnt(0)
	v_add_f32_e32 v85, v85, v104
	ds_bpermute_b32 v93, v93, v85
	v_addc_co_u32_e32 v127, vcc, 0, v35, vcc
	v_add_co_u32_e32 v134, vcc, s30, v102
	s_waitcnt lgkmcnt(0)
	v_add_f32_e32 v85, v85, v93
	ds_bpermute_b32 v93, v94, v85
	v_lshl_add_u64 v[32:33], v[102:103], 0, s[78:79]
	global_load_dwordx4 v[76:79], v[36:37], off
	global_load_dwordx4 v[80:83], v[34:35], off
	global_load_dwordx4 v[68:71], v[34:35], off offset:1024
	global_load_dwordx4 v[72:75], v[102:103], off
	global_load_dwordx4 v[60:63], v[102:103], off offset:1024
	global_load_dwordx4 v[64:67], v[32:33], off offset:1024
	global_load_dwordx4 v[52:55], v[32:33], off offset:2048
	global_load_dwordx4 v[56:59], v[34:35], off offset:2048
	global_load_dwordx4 v[44:47], v[34:35], off offset:3072
	global_load_dwordx4 v[48:51], v[102:103], off offset:2048
	global_load_dwordx4 v[36:39], v[102:103], off offset:3072
	global_load_dwordx4 v[40:43], v[32:33], off offset:3072
	v_addc_co_u32_e32 v135, vcc, 0, v103, vcc
	s_waitcnt lgkmcnt(0)
	v_add_f32_e32 v85, v85, v93
	ds_bpermute_b32 v93, v95, v85
	v_add_co_u32_e32 v130, vcc, s66, v102
	global_load_dwordx4 v[32:35], v[126:127], off
	global_load_dwordx4 v[106:109], v[126:127], off offset:1024
	v_addc_co_u32_e32 v131, vcc, 0, v103, vcc
	global_load_dwordx4 v[98:101], v[134:135], off
	global_load_dwordx4 v[102:105], v[130:131], off
	s_waitcnt lgkmcnt(0)
	v_add_f32_e32 v85, v85, v93
	ds_bpermute_b32 v93, v96, v85
	global_load_dwordx4 v[110:113], v[130:131], off offset:1024
	global_load_dwordx4 v[114:117], v[134:135], off offset:1024
	global_load_dwordx4 v[118:121], v[126:127], off offset:2048
	global_load_dwordx4 v[122:125], v[130:131], off offset:2048
	v_readlane_b32 s2, v253, 31
	v_readlane_b32 s3, v253, 32
	s_waitcnt lgkmcnt(0)
	v_add_f32_e32 v85, v85, v93
	ds_bpermute_b32 v93, v97, v85
	global_load_dwordx4 v[94:97], v[134:135], off offset:2048
	s_nop 0
	global_load_dwordx4 v[126:129], v[126:127], off offset:3072
	s_nop 0
	global_load_dwordx4 v[130:133], v[130:131], off offset:3072
	s_waitcnt lgkmcnt(0)
	v_add_f32_e32 v85, v85, v93
	global_load_dwordx4 v[134:137], v[134:135], off offset:3072
	v_fmamk_f32 v85, v85, 0x3a000000, v227
	v_mul_f32_e32 v93, 0x4b800000, v85
	v_cmp_gt_f32_e32 vcc, s96, v85
	s_waitcnt vmcnt(23)
	v_pk_add_f32 v[78:79], v[78:79], 1.0 op_sel_hi:[1,0]
	v_cndmask_b32_e32 v85, v85, v93, vcc
	v_rsq_f32_e32 v85, v85
	v_pk_add_f32 v[76:77], v[76:77], 1.0 op_sel_hi:[1,0]
	s_waitcnt vmcnt(18)
	v_pk_add_f32 v[66:67], v[66:67], 1.0 op_sel_hi:[1,0]
	v_mul_f32_e32 v93, 0x45800000, v85
	v_cndmask_b32_e32 v138, v85, v93, vcc
	v_pk_mul_f32 v[140:141], v[2:3], v[138:139] op_sel_hi:[1,0]
	v_pk_mul_f32 v[142:143], v[0:1], v[138:139] op_sel_hi:[1,0]
	v_pk_mul_f32 v[82:83], v[82:83], v[140:141]
	v_pk_mul_f32 v[80:81], v[80:81], v[142:143]
	v_pk_fma_f32 v[74:75], v[78:79], v[82:83], v[74:75]
	v_pk_fma_f32 v[72:73], v[76:77], v[80:81], v[72:73]
	v_pk_mul_f32 v[76:77], v[4:5], v[138:139] op_sel_hi:[1,0]
	v_cvt_pk_bf16_f32 v72, v72, v73
	v_cvt_pk_bf16_f32 v73, v74, v75
	v_pk_mul_f32 v[74:75], v[6:7], v[138:139] op_sel_hi:[1,0]
	v_pk_mul_f32 v[68:69], v[68:69], v[76:77]
	v_pk_mul_f32 v[70:71], v[70:71], v[74:75]
	v_pk_add_f32 v[64:65], v[64:65], 1.0 op_sel_hi:[1,0]
	v_pk_fma_f32 v[62:63], v[66:67], v[70:71], v[62:63]
	v_pk_fma_f32 v[60:61], v[64:65], v[68:69], v[60:61]
	v_pk_mul_f32 v[64:65], v[8:9], v[138:139] op_sel_hi:[1,0]
	v_cvt_pk_bf16_f32 v60, v60, v61
	v_cvt_pk_bf16_f32 v61, v62, v63
	v_pk_mul_f32 v[62:63], v[10:11], v[138:139] op_sel_hi:[1,0]
	s_waitcnt vmcnt(16)
	v_pk_mul_f32 v[56:57], v[56:57], v[64:65]
	v_pk_mul_f32 v[58:59], v[58:59], v[62:63]
	v_pk_add_f32 v[54:55], v[54:55], 1.0 op_sel_hi:[1,0]
	v_pk_add_f32 v[52:53], v[52:53], 1.0 op_sel_hi:[1,0]
	s_waitcnt vmcnt(14)
	v_pk_fma_f32 v[50:51], v[54:55], v[58:59], v[50:51]
	v_pk_fma_f32 v[48:49], v[52:53], v[56:57], v[48:49]
	v_pk_mul_f32 v[52:53], v[12:13], v[138:139] op_sel_hi:[1,0]
	v_cvt_pk_bf16_f32 v48, v48, v49
	v_cvt_pk_bf16_f32 v49, v50, v51
	v_pk_mul_f32 v[50:51], v[14:15], v[138:139] op_sel_hi:[1,0]
	v_pk_mul_f32 v[44:45], v[44:45], v[52:53]
	v_pk_mul_f32 v[46:47], v[46:47], v[50:51]
	s_waitcnt vmcnt(12)
	v_pk_add_f32 v[42:43], v[42:43], 1.0 op_sel_hi:[1,0]
	v_pk_add_f32 v[40:41], v[40:41], 1.0 op_sel_hi:[1,0]
	v_pk_fma_f32 v[38:39], v[42:43], v[46:47], v[38:39]
	v_pk_fma_f32 v[36:37], v[40:41], v[44:45], v[36:37]
	v_pk_mul_f32 v[40:41], v[16:17], v[138:139] op_sel_hi:[1,0]
	v_cvt_pk_bf16_f32 v36, v36, v37
	v_cvt_pk_bf16_f32 v37, v38, v39
	v_pk_mul_f32 v[38:39], v[18:19], v[138:139] op_sel_hi:[1,0]
	s_waitcnt vmcnt(11)
	v_pk_mul_f32 v[32:33], v[32:33], v[40:41]
	v_pk_mul_f32 v[34:35], v[34:35], v[38:39]
	s_waitcnt vmcnt(8)
	v_pk_add_f32 v[38:39], v[104:105], 1.0 op_sel_hi:[1,0]
	v_pk_add_f32 v[40:41], v[102:103], 1.0 op_sel_hi:[1,0]
	v_pk_fma_f32 v[34:35], v[38:39], v[34:35], v[100:101]
	v_pk_fma_f32 v[32:33], v[40:41], v[32:33], v[98:99]
	v_pk_mul_f32 v[38:39], v[20:21], v[138:139] op_sel_hi:[1,0]
	v_cvt_pk_bf16_f32 v32, v32, v33
	v_cvt_pk_bf16_f32 v33, v34, v35
	v_pk_mul_f32 v[34:35], v[22:23], v[138:139] op_sel_hi:[1,0]
	v_pk_mul_f32 v[38:39], v[106:107], v[38:39]
	v_pk_mul_f32 v[34:35], v[108:109], v[34:35]
	s_waitcnt vmcnt(7)
	v_pk_add_f32 v[40:41], v[112:113], 1.0 op_sel_hi:[1,0]
	v_pk_add_f32 v[42:43], v[110:111], 1.0 op_sel_hi:[1,0]
	s_waitcnt vmcnt(6)
	v_pk_fma_f32 v[34:35], v[40:41], v[34:35], v[116:117]
	v_pk_fma_f32 v[38:39], v[42:43], v[38:39], v[114:115]
	v_pk_mul_f32 v[40:41], v[24:25], v[138:139] op_sel_hi:[1,0]
	v_cvt_pk_bf16_f32 v38, v38, v39
	v_cvt_pk_bf16_f32 v39, v34, v35
	v_pk_mul_f32 v[34:35], v[26:27], v[138:139] op_sel_hi:[1,0]
	s_waitcnt vmcnt(5)
	v_pk_mul_f32 v[40:41], v[118:119], v[40:41]
	v_pk_mul_f32 v[34:35], v[120:121], v[34:35]
	s_waitcnt vmcnt(4)
	v_pk_add_f32 v[42:43], v[124:125], 1.0 op_sel_hi:[1,0]
	v_pk_add_f32 v[44:45], v[122:123], 1.0 op_sel_hi:[1,0]
	s_waitcnt vmcnt(3)
	v_pk_fma_f32 v[34:35], v[42:43], v[34:35], v[96:97]
	v_pk_fma_f32 v[40:41], v[44:45], v[40:41], v[94:95]
	v_pk_mul_f32 v[42:43], v[28:29], v[138:139] op_sel_hi:[1,0]
	v_cvt_pk_bf16_f32 v40, v40, v41
	v_cvt_pk_bf16_f32 v41, v34, v35
	v_pk_mul_f32 v[34:35], v[30:31], v[138:139] op_sel_hi:[1,0]
	s_waitcnt vmcnt(2)
	v_pk_mul_f32 v[42:43], v[126:127], v[42:43]
	v_pk_mul_f32 v[34:35], v[128:129], v[34:35]
	s_waitcnt vmcnt(1)
	v_pk_add_f32 v[44:45], v[132:133], 1.0 op_sel_hi:[1,0]
	v_pk_add_f32 v[46:47], v[130:131], 1.0 op_sel_hi:[1,0]
	s_waitcnt vmcnt(0)
	v_pk_fma_f32 v[34:35], v[44:45], v[34:35], v[136:137]
	v_pk_fma_f32 v[42:43], v[46:47], v[42:43], v[134:135]
	s_nop 0
	v_cvt_pk_bf16_f32 v42, v42, v43
	v_cvt_pk_bf16_f32 v43, v34, v35
	v_lshl_add_u64 v[34:35], s[2:3], 0, v[90:91]
	v_lshl_add_u64 v[34:35], v[88:89], 1, v[34:35]
	global_store_dwordx2 v[34:35], v[72:73], off
	global_store_dwordx2 v[34:35], v[60:61], off offset:512
	global_store_dwordx2 v[34:35], v[48:49], off offset:1024
	global_store_dwordx2 v[34:35], v[36:37], off offset:1536
	global_store_dwordx2 v[34:35], v[32:33], off offset:2048
	global_store_dwordx2 v[34:35], v[38:39], off offset:2560
	global_store_dwordx2 v[34:35], v[40:41], off offset:3072
	global_store_dwordx2 v[34:35], v[42:43], off offset:3584
	v_cvt_pk_bf16_f32 v0, v0, v1
	v_cvt_pk_bf16_f32 v1, v2, v3
	global_store_dwordx2 v[86:87], v[0:1], off nt
	v_cvt_pk_bf16_f32 v0, v4, v5
	v_cvt_pk_bf16_f32 v1, v6, v7
	global_store_dwordx2 v[86:87], v[0:1], off offset:512 nt
	v_cvt_pk_bf16_f32 v0, v8, v9
	v_cvt_pk_bf16_f32 v1, v10, v11
	global_store_dwordx2 v[86:87], v[0:1], off offset:1024 nt
	v_cvt_pk_bf16_f32 v0, v12, v13
	v_cvt_pk_bf16_f32 v1, v14, v15
	global_store_dwordx2 v[86:87], v[0:1], off offset:1536 nt
	v_cvt_pk_bf16_f32 v0, v16, v17
	v_cvt_pk_bf16_f32 v1, v18, v19
	global_store_dwordx2 v[86:87], v[0:1], off offset:2048 nt
	v_cvt_pk_bf16_f32 v0, v20, v21
	v_cvt_pk_bf16_f32 v1, v22, v23
	global_store_dwordx2 v[86:87], v[0:1], off offset:2560 nt
	v_cvt_pk_bf16_f32 v0, v24, v25
	v_cvt_pk_bf16_f32 v1, v26, v27
	global_store_dwordx2 v[86:87], v[0:1], off offset:3072 nt
	v_cvt_pk_bf16_f32 v0, v28, v29
	v_cvt_pk_bf16_f32 v1, v30, v31
	global_store_dwordx2 v[86:87], v[0:1], off offset:3584 nt
	s_branch .LBB0_295
